# combined: widened FFN1/gate epilogue stores + packed-f32 scan converter + rebalanced scan step order + single-round-trip scan reducer
# baseline (speedup 1.0000x reference)
.LBB0_1396:
	s_or_b64 exec, exec, s[2:3]
	v_cmp_ne_u32_e32 vcc, 4, v54
	v_lshrrev_b32_e32 v144, 5, v52
	v_mul_u32_u24_e32 v144, 0xc00, v144
	v_and_b32_e32 v49, 31, v52
	v_lshl_add_u32 v144, v49, 1, v144
	s_waitcnt vmcnt(0) lgkmcnt(0)
	s_barrier
	s_and_saveexec_b64 s[2:3], vcc
	s_xor_b64 s[2:3], exec, s[2:3]
	v_mov_b64_e32 v[50:51], v[144:145]
	s_or_saveexec_b64 s[2:3], s[2:3]
	v_lshlrev_b32_e32 v49, 5, v52
	v_add_u32_e32 v57, 0, v49
	s_xor_b64 exec, exec, s[2:3]
	s_cbranch_execz .LBB0_1400
	v_mov_b32_e32 v98, 1.0
	v_lshrrev_b32_e32 v63, 10, v57
	v_mul_u32_u24_e32 v63, 0x3000, v63
	v_bfe_u32 v99, v57, 5, 5
	v_lshl_add_u32 v63, v99, 3, v63
	v_mov_b32_e32 v99, 1.0
	v_mov_b32_e32 v72, 1.0
	v_mov_b32_e32 v73, 1.0
	v_lshlrev_b32_e32 v78, 16, v80
	v_and_b32_e32 v79, 0xffff0000, v80
	v_pk_add_f32 v[78:79], v[98:99], v[78:79] neg_lo:[0,1] neg_hi:[0,1]
	v_pk_mul_f32 v[72:73], v[72:73], v[78:79]
	v_lshlrev_b32_e32 v78, 16, v81
	v_and_b32_e32 v79, 0xffff0000, v81
	v_pk_add_f32 v[78:79], v[98:99], v[78:79] neg_lo:[0,1] neg_hi:[0,1]
	v_pk_mul_f32 v[72:73], v[72:73], v[78:79]
	v_lshlrev_b32_e32 v78, 16, v82
	v_and_b32_e32 v79, 0xffff0000, v82
	v_pk_add_f32 v[78:79], v[98:99], v[78:79] neg_lo:[0,1] neg_hi:[0,1]
	v_pk_mul_f32 v[72:73], v[72:73], v[78:79]
	v_lshlrev_b32_e32 v78, 16, v83
	v_and_b32_e32 v79, 0xffff0000, v83
	v_pk_add_f32 v[78:79], v[98:99], v[78:79] neg_lo:[0,1] neg_hi:[0,1]
	v_pk_mul_f32 v[72:73], v[72:73], v[78:79]
	v_lshlrev_b32_e32 v78, 16, v84
	v_and_b32_e32 v79, 0xffff0000, v84
	v_pk_add_f32 v[78:79], v[98:99], v[78:79] neg_lo:[0,1] neg_hi:[0,1]
	v_pk_mul_f32 v[72:73], v[72:73], v[78:79]
	v_lshlrev_b32_e32 v78, 16, v85
	v_and_b32_e32 v79, 0xffff0000, v85
	v_pk_add_f32 v[78:79], v[98:99], v[78:79] neg_lo:[0,1] neg_hi:[0,1]
	v_pk_mul_f32 v[72:73], v[72:73], v[78:79]
	v_lshlrev_b32_e32 v78, 16, v86
	v_and_b32_e32 v79, 0xffff0000, v86
	v_pk_add_f32 v[78:79], v[98:99], v[78:79] neg_lo:[0,1] neg_hi:[0,1]
	v_pk_mul_f32 v[72:73], v[72:73], v[78:79]
	v_lshlrev_b32_e32 v78, 16, v87
	v_and_b32_e32 v79, 0xffff0000, v87
	v_pk_add_f32 v[78:79], v[98:99], v[78:79] neg_lo:[0,1] neg_hi:[0,1]
	v_pk_mul_f32 v[72:73], v[72:73], v[78:79]
	v_cmp_gt_u32_e32 vcc, 0x400, v57
	s_nop 1
	v_cndmask_b32_e32 v72, v72, v98, vcc
	v_cndmask_b32_e32 v73, v73, v98, vcc
	v_lshlrev_b32_e32 v78, 16, v1
	v_and_b32_e32 v79, 0xffff0000, v1
	v_pk_add_f32 v[78:79], v[98:99], v[78:79] neg_lo:[0,1] neg_hi:[0,1]
	v_pk_mul_f32 v[74:75], v[72:73], v[78:79]
	v_lshlrev_b32_e32 v88, 16, v3
	v_and_b32_e32 v89, 0xffff0000, v3
	v_rcp_f32_e32 v76, v74
	v_rcp_f32_e32 v77, v75
	v_pk_mul_f32 v[88:89], v[88:89], v[72:73]
	v_lshlrev_b32_e32 v90, 16, v0
	v_and_b32_e32 v91, 0xffff0000, v0
	v_pk_mul_f32 v[90:91], v[90:91], v[74:75]
	v_lshlrev_b32_e32 v92, 16, v2
	v_and_b32_e32 v93, 0xffff0000, v2
	v_pk_mul_f32 v[92:93], v[92:93], v[76:77]
	v_lshlrev_b32_e32 v94, 16, v4
	v_and_b32_e32 v95, 0xffff0000, v4
	v_pk_mul_f32 v[94:95], v[94:95], v[76:77]
	v_lshlrev_b32_e32 v96, 16, v5
	v_and_b32_e32 v97, 0xffff0000, v5
	ds_write_b64 v63, v[90:91]
	ds_write_b64 v63, v[74:75] offset:256
	ds_write_b64 v63, v[92:93] offset:512
	ds_write_b64 v63, v[88:89] offset:768
	ds_write_b64 v63, v[94:95] offset:1024
	ds_write_b64 v63, v[96:97] offset:1280
	v_lshlrev_b32_e32 v78, 16, v7
	v_and_b32_e32 v79, 0xffff0000, v7
	v_pk_add_f32 v[78:79], v[98:99], v[78:79] neg_lo:[0,1] neg_hi:[0,1]
	v_pk_mul_f32 v[72:73], v[74:75], v[78:79]
	v_lshlrev_b32_e32 v88, 16, v9
	v_and_b32_e32 v89, 0xffff0000, v9
	v_rcp_f32_e32 v76, v72
	v_rcp_f32_e32 v77, v73
	v_pk_mul_f32 v[88:89], v[88:89], v[74:75]
	v_lshlrev_b32_e32 v90, 16, v6
	v_and_b32_e32 v91, 0xffff0000, v6
	v_pk_mul_f32 v[90:91], v[90:91], v[72:73]
	v_lshlrev_b32_e32 v92, 16, v8
	v_and_b32_e32 v93, 0xffff0000, v8
	v_pk_mul_f32 v[92:93], v[92:93], v[76:77]
	v_lshlrev_b32_e32 v94, 16, v10
	v_and_b32_e32 v95, 0xffff0000, v10
	v_pk_mul_f32 v[94:95], v[94:95], v[76:77]
	v_lshlrev_b32_e32 v96, 16, v11
	v_and_b32_e32 v97, 0xffff0000, v11
	ds_write_b64 v63, v[90:91] offset:1536
	ds_write_b64 v63, v[72:73] offset:1792
	ds_write_b64 v63, v[92:93] offset:2048
	ds_write_b64 v63, v[88:89] offset:2304
	ds_write_b64 v63, v[94:95] offset:2560
	ds_write_b64 v63, v[96:97] offset:2816
	v_lshlrev_b32_e32 v78, 16, v13
	v_and_b32_e32 v79, 0xffff0000, v13
	v_pk_add_f32 v[78:79], v[98:99], v[78:79] neg_lo:[0,1] neg_hi:[0,1]
	v_pk_mul_f32 v[74:75], v[72:73], v[78:79]
	v_lshlrev_b32_e32 v88, 16, v15
	v_and_b32_e32 v89, 0xffff0000, v15
	v_rcp_f32_e32 v76, v74
	v_rcp_f32_e32 v77, v75
	v_pk_mul_f32 v[88:89], v[88:89], v[72:73]
	v_lshlrev_b32_e32 v90, 16, v12
	v_and_b32_e32 v91, 0xffff0000, v12
	v_pk_mul_f32 v[90:91], v[90:91], v[74:75]
	v_lshlrev_b32_e32 v92, 16, v14
	v_and_b32_e32 v93, 0xffff0000, v14
	v_pk_mul_f32 v[92:93], v[92:93], v[76:77]
	v_lshlrev_b32_e32 v94, 16, v16
	v_and_b32_e32 v95, 0xffff0000, v16
	v_pk_mul_f32 v[94:95], v[94:95], v[76:77]
	v_lshlrev_b32_e32 v96, 16, v17
	v_and_b32_e32 v97, 0xffff0000, v17
	ds_write_b64 v63, v[90:91] offset:3072
	ds_write_b64 v63, v[74:75] offset:3328
	ds_write_b64 v63, v[92:93] offset:3584
	ds_write_b64 v63, v[88:89] offset:3840
	ds_write_b64 v63, v[94:95] offset:4096
	ds_write_b64 v63, v[96:97] offset:4352
	v_lshlrev_b32_e32 v78, 16, v19
	v_and_b32_e32 v79, 0xffff0000, v19
	v_pk_add_f32 v[78:79], v[98:99], v[78:79] neg_lo:[0,1] neg_hi:[0,1]
	v_pk_mul_f32 v[72:73], v[74:75], v[78:79]
	v_lshlrev_b32_e32 v88, 16, v21
	v_and_b32_e32 v89, 0xffff0000, v21
	v_rcp_f32_e32 v76, v72
	v_rcp_f32_e32 v77, v73
	v_pk_mul_f32 v[88:89], v[88:89], v[74:75]
	v_lshlrev_b32_e32 v90, 16, v18
	v_and_b32_e32 v91, 0xffff0000, v18
	v_pk_mul_f32 v[90:91], v[90:91], v[72:73]
	v_lshlrev_b32_e32 v92, 16, v20
	v_and_b32_e32 v93, 0xffff0000, v20
	v_pk_mul_f32 v[92:93], v[92:93], v[76:77]
	v_lshlrev_b32_e32 v94, 16, v22
	v_and_b32_e32 v95, 0xffff0000, v22
	v_pk_mul_f32 v[94:95], v[94:95], v[76:77]
	v_lshlrev_b32_e32 v96, 16, v23
	v_and_b32_e32 v97, 0xffff0000, v23
	ds_write_b64 v63, v[90:91] offset:4608
	ds_write_b64 v63, v[72:73] offset:4864
	ds_write_b64 v63, v[92:93] offset:5120
	ds_write_b64 v63, v[88:89] offset:5376
	ds_write_b64 v63, v[94:95] offset:5632
	ds_write_b64 v63, v[96:97] offset:5888
	v_lshlrev_b32_e32 v78, 16, v25
	v_and_b32_e32 v79, 0xffff0000, v25
	v_pk_add_f32 v[78:79], v[98:99], v[78:79] neg_lo:[0,1] neg_hi:[0,1]
	v_pk_mul_f32 v[74:75], v[72:73], v[78:79]
	v_lshlrev_b32_e32 v88, 16, v27
	v_and_b32_e32 v89, 0xffff0000, v27
	v_rcp_f32_e32 v76, v74
	v_rcp_f32_e32 v77, v75
	v_pk_mul_f32 v[88:89], v[88:89], v[72:73]
	v_lshlrev_b32_e32 v90, 16, v24
	v_and_b32_e32 v91, 0xffff0000, v24
	v_pk_mul_f32 v[90:91], v[90:91], v[74:75]
	v_lshlrev_b32_e32 v92, 16, v26
	v_and_b32_e32 v93, 0xffff0000, v26
	v_pk_mul_f32 v[92:93], v[92:93], v[76:77]
	v_lshlrev_b32_e32 v94, 16, v28
	v_and_b32_e32 v95, 0xffff0000, v28
	v_pk_mul_f32 v[94:95], v[94:95], v[76:77]
	v_lshlrev_b32_e32 v96, 16, v29
	v_and_b32_e32 v97, 0xffff0000, v29
	ds_write_b64 v63, v[90:91] offset:6144
	ds_write_b64 v63, v[74:75] offset:6400
	ds_write_b64 v63, v[92:93] offset:6656
	ds_write_b64 v63, v[88:89] offset:6912
	ds_write_b64 v63, v[94:95] offset:7168
	ds_write_b64 v63, v[96:97] offset:7424
	v_lshlrev_b32_e32 v78, 16, v31
	v_and_b32_e32 v79, 0xffff0000, v31
	v_pk_add_f32 v[78:79], v[98:99], v[78:79] neg_lo:[0,1] neg_hi:[0,1]
	v_pk_mul_f32 v[72:73], v[74:75], v[78:79]
	v_lshlrev_b32_e32 v88, 16, v33
	v_and_b32_e32 v89, 0xffff0000, v33
	v_rcp_f32_e32 v76, v72
	v_rcp_f32_e32 v77, v73
	v_pk_mul_f32 v[88:89], v[88:89], v[74:75]
	v_lshlrev_b32_e32 v90, 16, v30
	v_and_b32_e32 v91, 0xffff0000, v30
	v_pk_mul_f32 v[90:91], v[90:91], v[72:73]
	v_lshlrev_b32_e32 v92, 16, v32
	v_and_b32_e32 v93, 0xffff0000, v32
	v_pk_mul_f32 v[92:93], v[92:93], v[76:77]
	v_lshlrev_b32_e32 v94, 16, v34
	v_and_b32_e32 v95, 0xffff0000, v34
	v_pk_mul_f32 v[94:95], v[94:95], v[76:77]
	v_lshlrev_b32_e32 v96, 16, v35
	v_and_b32_e32 v97, 0xffff0000, v35
	ds_write_b64 v63, v[90:91] offset:7680
	ds_write_b64 v63, v[72:73] offset:7936
	ds_write_b64 v63, v[92:93] offset:8192
	ds_write_b64 v63, v[88:89] offset:8448
	ds_write_b64 v63, v[94:95] offset:8704
	ds_write_b64 v63, v[96:97] offset:8960
	v_lshlrev_b32_e32 v78, 16, v37
	v_and_b32_e32 v79, 0xffff0000, v37
	v_pk_add_f32 v[78:79], v[98:99], v[78:79] neg_lo:[0,1] neg_hi:[0,1]
	v_pk_mul_f32 v[74:75], v[72:73], v[78:79]
	v_lshlrev_b32_e32 v88, 16, v39
	v_and_b32_e32 v89, 0xffff0000, v39
	v_rcp_f32_e32 v76, v74
	v_rcp_f32_e32 v77, v75
	v_pk_mul_f32 v[88:89], v[88:89], v[72:73]
	v_lshlrev_b32_e32 v90, 16, v36
	v_and_b32_e32 v91, 0xffff0000, v36
	v_pk_mul_f32 v[90:91], v[90:91], v[74:75]
	v_lshlrev_b32_e32 v92, 16, v38
	v_and_b32_e32 v93, 0xffff0000, v38
	v_pk_mul_f32 v[92:93], v[92:93], v[76:77]
	v_lshlrev_b32_e32 v94, 16, v40
	v_and_b32_e32 v95, 0xffff0000, v40
	v_pk_mul_f32 v[94:95], v[94:95], v[76:77]
	v_lshlrev_b32_e32 v96, 16, v41
	v_and_b32_e32 v97, 0xffff0000, v41
	ds_write_b64 v63, v[90:91] offset:9216
	ds_write_b64 v63, v[74:75] offset:9472
	ds_write_b64 v63, v[92:93] offset:9728
	ds_write_b64 v63, v[88:89] offset:9984
	ds_write_b64 v63, v[94:95] offset:10240
	ds_write_b64 v63, v[96:97] offset:10496
	v_lshlrev_b32_e32 v78, 16, v43
	v_and_b32_e32 v79, 0xffff0000, v43
	v_pk_add_f32 v[78:79], v[98:99], v[78:79] neg_lo:[0,1] neg_hi:[0,1]
	v_pk_mul_f32 v[72:73], v[74:75], v[78:79]
	v_lshlrev_b32_e32 v88, 16, v45
	v_and_b32_e32 v89, 0xffff0000, v45
	v_rcp_f32_e32 v76, v72
	v_rcp_f32_e32 v77, v73
	v_pk_mul_f32 v[88:89], v[88:89], v[74:75]
	v_lshlrev_b32_e32 v90, 16, v42
	v_and_b32_e32 v91, 0xffff0000, v42
	v_pk_mul_f32 v[90:91], v[90:91], v[72:73]
	v_lshlrev_b32_e32 v92, 16, v44
	v_and_b32_e32 v93, 0xffff0000, v44
	v_pk_mul_f32 v[92:93], v[92:93], v[76:77]
	v_lshlrev_b32_e32 v94, 16, v46
	v_and_b32_e32 v95, 0xffff0000, v46
	v_pk_mul_f32 v[94:95], v[94:95], v[76:77]
	v_lshlrev_b32_e32 v96, 16, v47
	v_and_b32_e32 v97, 0xffff0000, v47
	ds_write_b64 v63, v[90:91] offset:10752
	ds_write_b64 v63, v[72:73] offset:11008
	ds_write_b64 v63, v[92:93] offset:11264
	ds_write_b64 v63, v[88:89] offset:11520
	ds_write_b64 v63, v[94:95] offset:11776
	ds_write_b64 v63, v[96:97] offset:12032
	v_lshrrev_b32_e32 v66, 5, v52
	v_mul_u32_u24_e32 v66, 0x1800, v66
	v_and_b32_e32 v67, 31, v52
	v_lshlrev_b32_e32 v67, 2, v67
	v_add_u32_e32 v64, v67, v66
	v_mov_b32_e32 v65, 0
	v_mov_b32_e32 v66, v67
	v_mov_b32_e32 v67, 0
	s_mov_b64 s[12:13], 0x9000
	v_lshl_add_u64 v[64:65], s[6:7], 0, v[64:65]
	v_lshl_add_u64 v[66:67], s[6:7], 0, v[66:67]
	v_lshl_add_u64 v[64:65], v[64:65], 0, s[12:13]
	v_lshl_add_u64 v[66:67], v[66:67], 0, s[12:13]
	s_movk_i32 s12, 0xf00
	s_mov_b32 s13, 0
	v_lshl_add_u64 v[68:69], v[64:65], 0, s[12:13]
	v_lshl_add_u64 v[70:71], v[66:67], 0, s[12:13]
	global_load_dword v0, v[64:65], off
	global_load_dword v1, v[64:65], off offset:128
	global_load_dword v2, v[64:65], off offset:256
	global_load_dword v3, v[64:65], off offset:384
	global_load_dword v4, v[64:65], off offset:512
	global_load_dword v5, v[64:65], off offset:640
	global_load_dword v6, v[64:65], off offset:768
	global_load_dword v7, v[64:65], off offset:896
	global_load_dword v8, v[64:65], off offset:1024
	global_load_dword v9, v[64:65], off offset:1152
	global_load_dword v10, v[64:65], off offset:1280
	global_load_dword v11, v[64:65], off offset:1408
	global_load_dword v12, v[64:65], off offset:1536
	global_load_dword v13, v[64:65], off offset:1664
	global_load_dword v14, v[64:65], off offset:1792
	global_load_dword v15, v[64:65], off offset:1920
	global_load_dword v16, v[64:65], off offset:2048
	global_load_dword v17, v[64:65], off offset:2176
	global_load_dword v18, v[64:65], off offset:2304
	global_load_dword v19, v[64:65], off offset:2432
	global_load_dword v20, v[64:65], off offset:2560
	global_load_dword v21, v[64:65], off offset:2688
	global_load_dword v22, v[64:65], off offset:2816
	global_load_dword v23, v[64:65], off offset:2944
	global_load_dword v24, v[64:65], off offset:3072
	global_load_dword v25, v[64:65], off offset:3200
	global_load_dword v26, v[64:65], off offset:3328
	global_load_dword v27, v[64:65], off offset:3456
	global_load_dword v28, v[64:65], off offset:3584
	global_load_dword v29, v[64:65], off offset:3712
	global_load_dword v30, v[64:65], off offset:3840
	global_load_dword v31, v[64:65], off offset:3968
	global_load_dword v32, v[68:69], off offset:256
	global_load_dword v33, v[68:69], off offset:384
	global_load_dword v34, v[68:69], off offset:512
	global_load_dword v35, v[68:69], off offset:640
	global_load_dword v36, v[68:69], off offset:768
	global_load_dword v37, v[68:69], off offset:896
	global_load_dword v38, v[68:69], off offset:1024
	global_load_dword v39, v[68:69], off offset:1152
	global_load_dword v40, v[68:69], off offset:1280
	global_load_dword v41, v[68:69], off offset:1408
	global_load_dword v42, v[68:69], off offset:1536
	global_load_dword v43, v[68:69], off offset:1664
	global_load_dword v44, v[68:69], off offset:1792
	global_load_dword v45, v[68:69], off offset:1920
	global_load_dword v46, v[68:69], off offset:2048
	global_load_dword v47, v[68:69], off offset:2176
	global_load_dword v80, v[66:67], off offset:128
	global_load_dword v81, v[66:67], off offset:896
	global_load_dword v82, v[66:67], off offset:1664
	global_load_dword v83, v[66:67], off offset:2432
	global_load_dword v84, v[66:67], off offset:3200
	global_load_dword v85, v[66:67], off offset:3968
	global_load_dword v86, v[70:71], off offset:896
	global_load_dword v87, v[70:71], off offset:1664
	v_mov_b64_e32 v[50:51], v[144:145]

; template <int MODE>
; __device__ __forceinline__ void rwkv_scan_unit(int wid_s, const bf16* SIbh_, bf16* Yb_, int ystride, int quarter, float* ldsf) {
;     ...
;         } else {
;             const int cn = ch + 1;
;             if (cn < 128 && (cn % 3) == hw) SCAN_CONVERT(cn);
;         }
.LBB0_1402:
	s_waitcnt lgkmcnt(0)
	s_barrier
	s_and_saveexec_b64 s[8:9], s[2:3]
	s_xor_b64 s[8:9], exec, s[8:9]
	s_cbranch_execz .LBB0_1412
	s_and_saveexec_b64 s[10:11], s[4:5]
	s_xor_b64 s[10:11], exec, s[10:11]
	s_cbranch_execz .LBB0_1408
	s_add_i32 s14, s0, 1
	v_readfirstlane_b32 s15, v56
	s_mul_i32 s17, s14, 0xab
	s_lshr_b32 s17, s17, 9
	s_mul_i32 s17, s17, 3
	s_sub_i32 s17, s14, s17
	s_cmp_lg_u32 s17, s15
	s_cbranch_scc1 .Lmy_cv_tryA
	s_cmp_gt_u32 s14, 0x7f
	s_cbranch_scc1 .Lmy_cv_done
	s_and_b32 s16, s14, 3
	s_mulk_i32 s16, 0x6000
	v_mov_b32_e32 v98, 1.0
	v_lshrrev_b32_e32 v63, 10, v57
	v_mul_u32_u24_e32 v63, 0x3000, v63
	v_bfe_u32 v99, v57, 5, 5
	v_lshl_add_u32 v63, v99, 3, v63
	v_add_u32_e32 v63, s16, v63
	s_cmp_lg_u32 s14, 1
	s_cbranch_scc1 .Lmy_cv_B
	s_waitcnt vmcnt(0)
	v_mov_b32_e32 v99, 1.0
	v_mov_b32_e32 v72, 1.0
	v_mov_b32_e32 v73, 1.0
	v_lshlrev_b32_e32 v78, 16, v80
	v_and_b32_e32 v79, 0xffff0000, v80
	v_pk_add_f32 v[78:79], v[98:99], v[78:79] neg_lo:[0,1] neg_hi:[0,1]
	v_pk_mul_f32 v[72:73], v[72:73], v[78:79]
	v_lshlrev_b32_e32 v78, 16, v81
	v_and_b32_e32 v79, 0xffff0000, v81
	v_pk_add_f32 v[78:79], v[98:99], v[78:79] neg_lo:[0,1] neg_hi:[0,1]
	v_pk_mul_f32 v[72:73], v[72:73], v[78:79]
	v_lshlrev_b32_e32 v78, 16, v82
	v_and_b32_e32 v79, 0xffff0000, v82
	v_pk_add_f32 v[78:79], v[98:99], v[78:79] neg_lo:[0,1] neg_hi:[0,1]
	v_pk_mul_f32 v[72:73], v[72:73], v[78:79]
	v_lshlrev_b32_e32 v78, 16, v83
	v_and_b32_e32 v79, 0xffff0000, v83
	v_pk_add_f32 v[78:79], v[98:99], v[78:79] neg_lo:[0,1] neg_hi:[0,1]
	v_pk_mul_f32 v[72:73], v[72:73], v[78:79]
	v_lshlrev_b32_e32 v78, 16, v84
	v_and_b32_e32 v79, 0xffff0000, v84
	v_pk_add_f32 v[78:79], v[98:99], v[78:79] neg_lo:[0,1] neg_hi:[0,1]
	v_pk_mul_f32 v[72:73], v[72:73], v[78:79]
	v_lshlrev_b32_e32 v78, 16, v85
	v_and_b32_e32 v79, 0xffff0000, v85
	v_pk_add_f32 v[78:79], v[98:99], v[78:79] neg_lo:[0,1] neg_hi:[0,1]
	v_pk_mul_f32 v[72:73], v[72:73], v[78:79]
	v_lshlrev_b32_e32 v78, 16, v86
	v_and_b32_e32 v79, 0xffff0000, v86
	v_pk_add_f32 v[78:79], v[98:99], v[78:79] neg_lo:[0,1] neg_hi:[0,1]
	v_pk_mul_f32 v[72:73], v[72:73], v[78:79]
	v_lshlrev_b32_e32 v78, 16, v87
	v_and_b32_e32 v79, 0xffff0000, v87
	v_pk_add_f32 v[78:79], v[98:99], v[78:79] neg_lo:[0,1] neg_hi:[0,1]
	v_pk_mul_f32 v[72:73], v[72:73], v[78:79]
	v_cmp_gt_u32_e32 vcc, 0x400, v57
	s_nop 1
	v_cndmask_b32_e32 v72, v72, v98, vcc
	v_cndmask_b32_e32 v73, v73, v98, vcc
	v_lshlrev_b32_e32 v78, 16, v1
	v_and_b32_e32 v79, 0xffff0000, v1
	v_pk_add_f32 v[78:79], v[98:99], v[78:79] neg_lo:[0,1] neg_hi:[0,1]
	v_pk_mul_f32 v[74:75], v[72:73], v[78:79]
	v_lshlrev_b32_e32 v88, 16, v3
	v_and_b32_e32 v89, 0xffff0000, v3
	v_rcp_f32_e32 v76, v74
	v_rcp_f32_e32 v77, v75
	v_pk_mul_f32 v[88:89], v[88:89], v[72:73]
	v_lshlrev_b32_e32 v90, 16, v0
	v_and_b32_e32 v91, 0xffff0000, v0
	v_pk_mul_f32 v[90:91], v[90:91], v[74:75]
	v_lshlrev_b32_e32 v92, 16, v2
	v_and_b32_e32 v93, 0xffff0000, v2
	v_pk_mul_f32 v[92:93], v[92:93], v[76:77]
	v_lshlrev_b32_e32 v94, 16, v4
	v_and_b32_e32 v95, 0xffff0000, v4
	v_pk_mul_f32 v[94:95], v[94:95], v[76:77]
	v_lshlrev_b32_e32 v96, 16, v5
	v_and_b32_e32 v97, 0xffff0000, v5
	ds_write_b64 v63, v[90:91]
	ds_write_b64 v63, v[74:75] offset:256
	ds_write_b64 v63, v[92:93] offset:512
	ds_write_b64 v63, v[88:89] offset:768
	ds_write_b64 v63, v[94:95] offset:1024
	ds_write_b64 v63, v[96:97] offset:1280
	v_lshlrev_b32_e32 v78, 16, v7
	v_and_b32_e32 v79, 0xffff0000, v7
	v_pk_add_f32 v[78:79], v[98:99], v[78:79] neg_lo:[0,1] neg_hi:[0,1]
	v_pk_mul_f32 v[72:73], v[74:75], v[78:79]
	v_lshlrev_b32_e32 v88, 16, v9
	v_and_b32_e32 v89, 0xffff0000, v9
	v_rcp_f32_e32 v76, v72
	v_rcp_f32_e32 v77, v73
	v_pk_mul_f32 v[88:89], v[88:89], v[74:75]
	v_lshlrev_b32_e32 v90, 16, v6
	v_and_b32_e32 v91, 0xffff0000, v6
	v_pk_mul_f32 v[90:91], v[90:91], v[72:73]
	v_lshlrev_b32_e32 v92, 16, v8
	v_and_b32_e32 v93, 0xffff0000, v8
	v_pk_mul_f32 v[92:93], v[92:93], v[76:77]
	v_lshlrev_b32_e32 v94, 16, v10
	v_and_b32_e32 v95, 0xffff0000, v10
	v_pk_mul_f32 v[94:95], v[94:95], v[76:77]
	v_lshlrev_b32_e32 v96, 16, v11
	v_and_b32_e32 v97, 0xffff0000, v11
	ds_write_b64 v63, v[90:91] offset:1536
	ds_write_b64 v63, v[72:73] offset:1792
	ds_write_b64 v63, v[92:93] offset:2048
	ds_write_b64 v63, v[88:89] offset:2304
	ds_write_b64 v63, v[94:95] offset:2560
	ds_write_b64 v63, v[96:97] offset:2816
	v_lshlrev_b32_e32 v78, 16, v13
	v_and_b32_e32 v79, 0xffff0000, v13
	v_pk_add_f32 v[78:79], v[98:99], v[78:79] neg_lo:[0,1] neg_hi:[0,1]
	v_pk_mul_f32 v[74:75], v[72:73], v[78:79]
	v_lshlrev_b32_e32 v88, 16, v15
	v_and_b32_e32 v89, 0xffff0000, v15
	v_rcp_f32_e32 v76, v74
	v_rcp_f32_e32 v77, v75
	v_pk_mul_f32 v[88:89], v[88:89], v[72:73]
	v_lshlrev_b32_e32 v90, 16, v12
	v_and_b32_e32 v91, 0xffff0000, v12
	v_pk_mul_f32 v[90:91], v[90:91], v[74:75]
	v_lshlrev_b32_e32 v92, 16, v14
	v_and_b32_e32 v93, 0xffff0000, v14
	v_pk_mul_f32 v[92:93], v[92:93], v[76:77]
	v_lshlrev_b32_e32 v94, 16, v16
	v_and_b32_e32 v95, 0xffff0000, v16
	v_pk_mul_f32 v[94:95], v[94:95], v[76:77]
	v_lshlrev_b32_e32 v96, 16, v17
	v_and_b32_e32 v97, 0xffff0000, v17
	ds_write_b64 v63, v[90:91] offset:3072
	ds_write_b64 v63, v[74:75] offset:3328
	ds_write_b64 v63, v[92:93] offset:3584
	ds_write_b64 v63, v[88:89] offset:3840
	ds_write_b64 v63, v[94:95] offset:4096
	ds_write_b64 v63, v[96:97] offset:4352
	v_lshlrev_b32_e32 v78, 16, v19
	v_and_b32_e32 v79, 0xffff0000, v19
	v_pk_add_f32 v[78:79], v[98:99], v[78:79] neg_lo:[0,1] neg_hi:[0,1]
	v_pk_mul_f32 v[72:73], v[74:75], v[78:79]
	v_lshlrev_b32_e32 v88, 16, v21
	v_and_b32_e32 v89, 0xffff0000, v21
	v_rcp_f32_e32 v76, v72
	v_rcp_f32_e32 v77, v73
	v_pk_mul_f32 v[88:89], v[88:89], v[74:75]
	v_lshlrev_b32_e32 v90, 16, v18
	v_and_b32_e32 v91, 0xffff0000, v18
	v_pk_mul_f32 v[90:91], v[90:91], v[72:73]
	v_lshlrev_b32_e32 v92, 16, v20
	v_and_b32_e32 v93, 0xffff0000, v20
	v_pk_mul_f32 v[92:93], v[92:93], v[76:77]
	v_lshlrev_b32_e32 v94, 16, v22
	v_and_b32_e32 v95, 0xffff0000, v22
	v_pk_mul_f32 v[94:95], v[94:95], v[76:77]
	v_lshlrev_b32_e32 v96, 16, v23
	v_and_b32_e32 v97, 0xffff0000, v23
	ds_write_b64 v63, v[90:91] offset:4608
	ds_write_b64 v63, v[72:73] offset:4864
	ds_write_b64 v63, v[92:93] offset:5120
	ds_write_b64 v63, v[88:89] offset:5376
	ds_write_b64 v63, v[94:95] offset:5632
	ds_write_b64 v63, v[96:97] offset:5888
.Lmy_cv_B:
	v_mov_b32_e32 v99, 1.0
	v_lshlrev_b32_e32 v78, 16, v25
	v_and_b32_e32 v79, 0xffff0000, v25
	v_pk_add_f32 v[78:79], v[98:99], v[78:79] neg_lo:[0,1] neg_hi:[0,1]
	v_pk_mul_f32 v[74:75], v[72:73], v[78:79]
	v_lshlrev_b32_e32 v88, 16, v27
	v_and_b32_e32 v89, 0xffff0000, v27
	v_rcp_f32_e32 v76, v74
	v_rcp_f32_e32 v77, v75
	v_pk_mul_f32 v[88:89], v[88:89], v[72:73]
	v_lshlrev_b32_e32 v90, 16, v24
	v_and_b32_e32 v91, 0xffff0000, v24
	v_pk_mul_f32 v[90:91], v[90:91], v[74:75]
	v_lshlrev_b32_e32 v92, 16, v26
	v_and_b32_e32 v93, 0xffff0000, v26
	v_pk_mul_f32 v[92:93], v[92:93], v[76:77]
	v_lshlrev_b32_e32 v94, 16, v28
	v_and_b32_e32 v95, 0xffff0000, v28
	v_pk_mul_f32 v[94:95], v[94:95], v[76:77]
	v_lshlrev_b32_e32 v96, 16, v29
	v_and_b32_e32 v97, 0xffff0000, v29
	ds_write_b64 v63, v[90:91] offset:6144
	ds_write_b64 v63, v[74:75] offset:6400
	ds_write_b64 v63, v[92:93] offset:6656
	ds_write_b64 v63, v[88:89] offset:6912
	ds_write_b64 v63, v[94:95] offset:7168
	ds_write_b64 v63, v[96:97] offset:7424
	v_lshlrev_b32_e32 v78, 16, v31
	v_and_b32_e32 v79, 0xffff0000, v31
	v_pk_add_f32 v[78:79], v[98:99], v[78:79] neg_lo:[0,1] neg_hi:[0,1]
	v_pk_mul_f32 v[72:73], v[74:75], v[78:79]
	v_lshlrev_b32_e32 v88, 16, v33
	v_and_b32_e32 v89, 0xffff0000, v33
	v_rcp_f32_e32 v76, v72
	v_rcp_f32_e32 v77, v73
	v_pk_mul_f32 v[88:89], v[88:89], v[74:75]
	v_lshlrev_b32_e32 v90, 16, v30
	v_and_b32_e32 v91, 0xffff0000, v30
	v_pk_mul_f32 v[90:91], v[90:91], v[72:73]
	v_lshlrev_b32_e32 v92, 16, v32
	v_and_b32_e32 v93, 0xffff0000, v32
	v_pk_mul_f32 v[92:93], v[92:93], v[76:77]
	v_lshlrev_b32_e32 v94, 16, v34
	v_and_b32_e32 v95, 0xffff0000, v34
	v_pk_mul_f32 v[94:95], v[94:95], v[76:77]
	v_lshlrev_b32_e32 v96, 16, v35
	v_and_b32_e32 v97, 0xffff0000, v35
	ds_write_b64 v63, v[90:91] offset:7680
	ds_write_b64 v63, v[72:73] offset:7936
	ds_write_b64 v63, v[92:93] offset:8192
	ds_write_b64 v63, v[88:89] offset:8448
	ds_write_b64 v63, v[94:95] offset:8704
	ds_write_b64 v63, v[96:97] offset:8960
	v_lshlrev_b32_e32 v78, 16, v37
	v_and_b32_e32 v79, 0xffff0000, v37
	v_pk_add_f32 v[78:79], v[98:99], v[78:79] neg_lo:[0,1] neg_hi:[0,1]
	v_pk_mul_f32 v[74:75], v[72:73], v[78:79]
	v_lshlrev_b32_e32 v88, 16, v39
	v_and_b32_e32 v89, 0xffff0000, v39
	v_rcp_f32_e32 v76, v74
	v_rcp_f32_e32 v77, v75
	v_pk_mul_f32 v[88:89], v[88:89], v[72:73]
	v_lshlrev_b32_e32 v90, 16, v36
	v_and_b32_e32 v91, 0xffff0000, v36
	v_pk_mul_f32 v[90:91], v[90:91], v[74:75]
	v_lshlrev_b32_e32 v92, 16, v38
	v_and_b32_e32 v93, 0xffff0000, v38
	v_pk_mul_f32 v[92:93], v[92:93], v[76:77]
	v_lshlrev_b32_e32 v94, 16, v40
	v_and_b32_e32 v95, 0xffff0000, v40
	v_pk_mul_f32 v[94:95], v[94:95], v[76:77]
	v_lshlrev_b32_e32 v96, 16, v41
	v_and_b32_e32 v97, 0xffff0000, v41
	ds_write_b64 v63, v[90:91] offset:9216
	ds_write_b64 v63, v[74:75] offset:9472
	ds_write_b64 v63, v[92:93] offset:9728
	ds_write_b64 v63, v[88:89] offset:9984
	ds_write_b64 v63, v[94:95] offset:10240
	ds_write_b64 v63, v[96:97] offset:10496
	v_lshlrev_b32_e32 v78, 16, v43
	v_and_b32_e32 v79, 0xffff0000, v43
	v_pk_add_f32 v[78:79], v[98:99], v[78:79] neg_lo:[0,1] neg_hi:[0,1]
	v_pk_mul_f32 v[72:73], v[74:75], v[78:79]
	v_lshlrev_b32_e32 v88, 16, v45
	v_and_b32_e32 v89, 0xffff0000, v45
	v_rcp_f32_e32 v76, v72
	v_rcp_f32_e32 v77, v73
	v_pk_mul_f32 v[88:89], v[88:89], v[74:75]
	v_lshlrev_b32_e32 v90, 16, v42
	v_and_b32_e32 v91, 0xffff0000, v42
	v_pk_mul_f32 v[90:91], v[90:91], v[72:73]
	v_lshlrev_b32_e32 v92, 16, v44
	v_and_b32_e32 v93, 0xffff0000, v44
	v_pk_mul_f32 v[92:93], v[92:93], v[76:77]
	v_lshlrev_b32_e32 v94, 16, v46
	v_and_b32_e32 v95, 0xffff0000, v46
	v_pk_mul_f32 v[94:95], v[94:95], v[76:77]
	v_lshlrev_b32_e32 v96, 16, v47
	v_and_b32_e32 v97, 0xffff0000, v47
	ds_write_b64 v63, v[90:91] offset:10752
	ds_write_b64 v63, v[72:73] offset:11008
	ds_write_b64 v63, v[92:93] offset:11264
	ds_write_b64 v63, v[88:89] offset:11520
	ds_write_b64 v63, v[94:95] offset:11776
	ds_write_b64 v63, v[96:97] offset:12032
	s_add_i32 s16, s14, 3
	s_cmp_gt_u32 s16, 0x7f
	s_cbranch_scc1 .Lmy_cv_done
	s_mul_i32 s12, s16, 0x3000
	s_mov_b32 s13, 0
	v_lshl_add_u64 v[64:65], v[50:51], 0, s[12:13]
	v_lshrrev_b32_e32 v66, 10, v57
	v_mul_u32_u24_e32 v66, 0x1800, v66
	v_mov_b32_e32 v67, 0
	v_sub_co_u32_e32 v66, vcc, v64, v66
	s_nop 1
	v_subb_co_u32_e32 v67, vcc, v65, v67, vcc
	s_movk_i32 s14, 0xf00
	s_mov_b32 s15, 0
	v_lshl_add_u64 v[68:69], v[64:65], 0, s[14:15]
	v_lshl_add_u64 v[70:71], v[66:67], 0, s[14:15]
	global_load_dword v0, v[64:65], off
	global_load_dword v1, v[64:65], off offset:128
	global_load_dword v2, v[64:65], off offset:256
	global_load_dword v3, v[64:65], off offset:384
	global_load_dword v4, v[64:65], off offset:512
	global_load_dword v5, v[64:65], off offset:640
	global_load_dword v6, v[64:65], off offset:768
	global_load_dword v7, v[64:65], off offset:896
	global_load_dword v8, v[64:65], off offset:1024
	global_load_dword v9, v[64:65], off offset:1152
	global_load_dword v10, v[64:65], off offset:1280
	global_load_dword v11, v[64:65], off offset:1408
	global_load_dword v12, v[64:65], off offset:1536
	global_load_dword v13, v[64:65], off offset:1664
	global_load_dword v14, v[64:65], off offset:1792
	global_load_dword v15, v[64:65], off offset:1920
	global_load_dword v16, v[64:65], off offset:2048
	global_load_dword v17, v[64:65], off offset:2176
	global_load_dword v18, v[64:65], off offset:2304
	global_load_dword v19, v[64:65], off offset:2432
	global_load_dword v20, v[64:65], off offset:2560
	global_load_dword v21, v[64:65], off offset:2688
	global_load_dword v22, v[64:65], off offset:2816
	global_load_dword v23, v[64:65], off offset:2944
	global_load_dword v24, v[64:65], off offset:3072
	global_load_dword v25, v[64:65], off offset:3200
	global_load_dword v26, v[64:65], off offset:3328
	global_load_dword v27, v[64:65], off offset:3456
	global_load_dword v28, v[64:65], off offset:3584
	global_load_dword v29, v[64:65], off offset:3712
	global_load_dword v30, v[64:65], off offset:3840
	global_load_dword v31, v[64:65], off offset:3968
	global_load_dword v32, v[68:69], off offset:256
	global_load_dword v33, v[68:69], off offset:384
	global_load_dword v34, v[68:69], off offset:512
	global_load_dword v35, v[68:69], off offset:640
	global_load_dword v36, v[68:69], off offset:768
	global_load_dword v37, v[68:69], off offset:896
	global_load_dword v38, v[68:69], off offset:1024
	global_load_dword v39, v[68:69], off offset:1152
	global_load_dword v40, v[68:69], off offset:1280
	global_load_dword v41, v[68:69], off offset:1408
	global_load_dword v42, v[68:69], off offset:1536
	global_load_dword v43, v[68:69], off offset:1664
	global_load_dword v44, v[68:69], off offset:1792
	global_load_dword v45, v[68:69], off offset:1920
	global_load_dword v46, v[68:69], off offset:2048
	global_load_dword v47, v[68:69], off offset:2176
	global_load_dword v80, v[66:67], off offset:128
	global_load_dword v81, v[66:67], off offset:896
	global_load_dword v82, v[66:67], off offset:1664
	global_load_dword v83, v[66:67], off offset:2432
	global_load_dword v84, v[66:67], off offset:3200
	global_load_dword v85, v[66:67], off offset:3968
	global_load_dword v86, v[70:71], off offset:896
	global_load_dword v87, v[70:71], off offset:1664
	s_branch .Lmy_cv_done
; template <int MODE>
; __device__ __forceinline__ void rwkv_scan_unit(int wid_s, const bf16* SIbh_, bf16* Yb_, int ystride, int quarter, float* ldsf) {
;     ...
;         } else {
;             const int cn = ch + 1;
;             if (cn < 128 && (cn % 3) == hw) SCAN_CONVERT(cn);
;         }
.Lmy_cv_tryA:
	s_add_i32 s17, s17, 1
	s_cmp_eq_u32 s17, 3
	s_cselect_b32 s17, 0, s17
	s_cmp_lg_u32 s17, s15
	s_cbranch_scc1 .Lmy_cv_done
	s_add_i32 s16, s14, 1
	s_cmp_gt_u32 s16, 0x7f
	s_cbranch_scc1 .Lmy_cv_done
	s_and_b32 s16, s16, 3
	s_mulk_i32 s16, 0x6000
	v_mov_b32_e32 v98, 1.0
	v_lshrrev_b32_e32 v63, 10, v57
	v_mul_u32_u24_e32 v63, 0x3000, v63
	v_bfe_u32 v99, v57, 5, 5
	v_lshl_add_u32 v63, v99, 3, v63
	v_add_u32_e32 v63, s16, v63
	s_waitcnt vmcnt(0)
	v_mov_b32_e32 v99, 1.0
	v_mov_b32_e32 v72, 1.0
	v_mov_b32_e32 v73, 1.0
	v_lshlrev_b32_e32 v78, 16, v80
	v_and_b32_e32 v79, 0xffff0000, v80
	v_pk_add_f32 v[78:79], v[98:99], v[78:79] neg_lo:[0,1] neg_hi:[0,1]
	v_pk_mul_f32 v[72:73], v[72:73], v[78:79]
	v_lshlrev_b32_e32 v78, 16, v81
	v_and_b32_e32 v79, 0xffff0000, v81
	v_pk_add_f32 v[78:79], v[98:99], v[78:79] neg_lo:[0,1] neg_hi:[0,1]
	v_pk_mul_f32 v[72:73], v[72:73], v[78:79]
	v_lshlrev_b32_e32 v78, 16, v82
	v_and_b32_e32 v79, 0xffff0000, v82
	v_pk_add_f32 v[78:79], v[98:99], v[78:79] neg_lo:[0,1] neg_hi:[0,1]
	v_pk_mul_f32 v[72:73], v[72:73], v[78:79]
	v_lshlrev_b32_e32 v78, 16, v83
	v_and_b32_e32 v79, 0xffff0000, v83
	v_pk_add_f32 v[78:79], v[98:99], v[78:79] neg_lo:[0,1] neg_hi:[0,1]
	v_pk_mul_f32 v[72:73], v[72:73], v[78:79]
	v_lshlrev_b32_e32 v78, 16, v84
	v_and_b32_e32 v79, 0xffff0000, v84
	v_pk_add_f32 v[78:79], v[98:99], v[78:79] neg_lo:[0,1] neg_hi:[0,1]
	v_pk_mul_f32 v[72:73], v[72:73], v[78:79]
	v_lshlrev_b32_e32 v78, 16, v85
	v_and_b32_e32 v79, 0xffff0000, v85
	v_pk_add_f32 v[78:79], v[98:99], v[78:79] neg_lo:[0,1] neg_hi:[0,1]
	v_pk_mul_f32 v[72:73], v[72:73], v[78:79]
	v_lshlrev_b32_e32 v78, 16, v86
	v_and_b32_e32 v79, 0xffff0000, v86
	v_pk_add_f32 v[78:79], v[98:99], v[78:79] neg_lo:[0,1] neg_hi:[0,1]
	v_pk_mul_f32 v[72:73], v[72:73], v[78:79]
	v_lshlrev_b32_e32 v78, 16, v87
	v_and_b32_e32 v79, 0xffff0000, v87
	v_pk_add_f32 v[78:79], v[98:99], v[78:79] neg_lo:[0,1] neg_hi:[0,1]
	v_pk_mul_f32 v[72:73], v[72:73], v[78:79]
	v_cmp_gt_u32_e32 vcc, 0x400, v57
	s_nop 1
	v_cndmask_b32_e32 v72, v72, v98, vcc
	v_cndmask_b32_e32 v73, v73, v98, vcc
	v_lshlrev_b32_e32 v78, 16, v1
	v_and_b32_e32 v79, 0xffff0000, v1
	v_pk_add_f32 v[78:79], v[98:99], v[78:79] neg_lo:[0,1] neg_hi:[0,1]
	v_pk_mul_f32 v[74:75], v[72:73], v[78:79]
	v_lshlrev_b32_e32 v88, 16, v3
	v_and_b32_e32 v89, 0xffff0000, v3
	v_rcp_f32_e32 v76, v74
	v_rcp_f32_e32 v77, v75
	v_pk_mul_f32 v[88:89], v[88:89], v[72:73]
	v_lshlrev_b32_e32 v90, 16, v0
	v_and_b32_e32 v91, 0xffff0000, v0
	v_pk_mul_f32 v[90:91], v[90:91], v[74:75]
	v_lshlrev_b32_e32 v92, 16, v2
	v_and_b32_e32 v93, 0xffff0000, v2
	v_pk_mul_f32 v[92:93], v[92:93], v[76:77]
	v_lshlrev_b32_e32 v94, 16, v4
	v_and_b32_e32 v95, 0xffff0000, v4
	v_pk_mul_f32 v[94:95], v[94:95], v[76:77]
	v_lshlrev_b32_e32 v96, 16, v5
	v_and_b32_e32 v97, 0xffff0000, v5
	ds_write_b64 v63, v[90:91]
	ds_write_b64 v63, v[74:75] offset:256
	ds_write_b64 v63, v[92:93] offset:512
	ds_write_b64 v63, v[88:89] offset:768
	ds_write_b64 v63, v[94:95] offset:1024
	ds_write_b64 v63, v[96:97] offset:1280
	v_lshlrev_b32_e32 v78, 16, v7
	v_and_b32_e32 v79, 0xffff0000, v7
	v_pk_add_f32 v[78:79], v[98:99], v[78:79] neg_lo:[0,1] neg_hi:[0,1]
	v_pk_mul_f32 v[72:73], v[74:75], v[78:79]
	v_lshlrev_b32_e32 v88, 16, v9
	v_and_b32_e32 v89, 0xffff0000, v9
	v_rcp_f32_e32 v76, v72
	v_rcp_f32_e32 v77, v73
	v_pk_mul_f32 v[88:89], v[88:89], v[74:75]
	v_lshlrev_b32_e32 v90, 16, v6
	v_and_b32_e32 v91, 0xffff0000, v6
	v_pk_mul_f32 v[90:91], v[90:91], v[72:73]
	v_lshlrev_b32_e32 v92, 16, v8
	v_and_b32_e32 v93, 0xffff0000, v8
	v_pk_mul_f32 v[92:93], v[92:93], v[76:77]
	v_lshlrev_b32_e32 v94, 16, v10
	v_and_b32_e32 v95, 0xffff0000, v10
	v_pk_mul_f32 v[94:95], v[94:95], v[76:77]
	v_lshlrev_b32_e32 v96, 16, v11
	v_and_b32_e32 v97, 0xffff0000, v11
	ds_write_b64 v63, v[90:91] offset:1536
	ds_write_b64 v63, v[72:73] offset:1792
	ds_write_b64 v63, v[92:93] offset:2048
	ds_write_b64 v63, v[88:89] offset:2304
	ds_write_b64 v63, v[94:95] offset:2560
	ds_write_b64 v63, v[96:97] offset:2816
	v_lshlrev_b32_e32 v78, 16, v13
	v_and_b32_e32 v79, 0xffff0000, v13
	v_pk_add_f32 v[78:79], v[98:99], v[78:79] neg_lo:[0,1] neg_hi:[0,1]
	v_pk_mul_f32 v[74:75], v[72:73], v[78:79]
	v_lshlrev_b32_e32 v88, 16, v15
	v_and_b32_e32 v89, 0xffff0000, v15
	v_rcp_f32_e32 v76, v74
	v_rcp_f32_e32 v77, v75
	v_pk_mul_f32 v[88:89], v[88:89], v[72:73]
	v_lshlrev_b32_e32 v90, 16, v12
	v_and_b32_e32 v91, 0xffff0000, v12
	v_pk_mul_f32 v[90:91], v[90:91], v[74:75]
	v_lshlrev_b32_e32 v92, 16, v14
	v_and_b32_e32 v93, 0xffff0000, v14
	v_pk_mul_f32 v[92:93], v[92:93], v[76:77]
	v_lshlrev_b32_e32 v94, 16, v16
	v_and_b32_e32 v95, 0xffff0000, v16
	v_pk_mul_f32 v[94:95], v[94:95], v[76:77]
	v_lshlrev_b32_e32 v96, 16, v17
	v_and_b32_e32 v97, 0xffff0000, v17
	ds_write_b64 v63, v[90:91] offset:3072
	ds_write_b64 v63, v[74:75] offset:3328
	ds_write_b64 v63, v[92:93] offset:3584
	ds_write_b64 v63, v[88:89] offset:3840
	ds_write_b64 v63, v[94:95] offset:4096
	ds_write_b64 v63, v[96:97] offset:4352
	v_lshlrev_b32_e32 v78, 16, v19
	v_and_b32_e32 v79, 0xffff0000, v19
	v_pk_add_f32 v[78:79], v[98:99], v[78:79] neg_lo:[0,1] neg_hi:[0,1]
	v_pk_mul_f32 v[72:73], v[74:75], v[78:79]
	v_lshlrev_b32_e32 v88, 16, v21
	v_and_b32_e32 v89, 0xffff0000, v21
	v_rcp_f32_e32 v76, v72
	v_rcp_f32_e32 v77, v73
	v_pk_mul_f32 v[88:89], v[88:89], v[74:75]
	v_lshlrev_b32_e32 v90, 16, v18
	v_and_b32_e32 v91, 0xffff0000, v18
	v_pk_mul_f32 v[90:91], v[90:91], v[72:73]
	v_lshlrev_b32_e32 v92, 16, v20
	v_and_b32_e32 v93, 0xffff0000, v20
	v_pk_mul_f32 v[92:93], v[92:93], v[76:77]
	v_lshlrev_b32_e32 v94, 16, v22
	v_and_b32_e32 v95, 0xffff0000, v22
	v_pk_mul_f32 v[94:95], v[94:95], v[76:77]
	v_lshlrev_b32_e32 v96, 16, v23
	v_and_b32_e32 v97, 0xffff0000, v23
	ds_write_b64 v63, v[90:91] offset:4608
	ds_write_b64 v63, v[72:73] offset:4864
	ds_write_b64 v63, v[92:93] offset:5120
	ds_write_b64 v63, v[88:89] offset:5376
	ds_write_b64 v63, v[94:95] offset:5632
	ds_write_b64 v63, v[96:97] offset:5888

; __device__ __forceinline__ float allreduce16(float x) { x += dppf<0xB1>(x); x += dppf<0x4E>(x); x += dppf<0x141>(x); x += dppf<0x140>(x); return x; }
; template <int MODE>
; __device__ __forceinline__ void rwkv_scan_unit(int wid_s, const bf16* SIbh_, bf16* Yb_, int ystride, int quarter, float* ldsf) {
;     ...
;         if (wv < 4) {
;             if (ch < 128) {
;                 const float* B = ldsf + (ch & 3) * (16 * 384);
;                 float* PY = PYb + (ch & 1) * (16 * 260) + wv * 64 + lane;
;                 const float* q = B;
;                 f32x4 r4 = *(const f32x4*)(q + c4), om4 = *(const f32x4*)(q + 64 + c4), k4 = *(const f32x4*)(q + 128 + c4), kk4 = *(const f32x4*)(q + 192 + c4), ka4 = *(const f32x4*)(q + 256 + c4);
;                 float v = q[320 + rowl];
;                 __builtin_amdgcn_s_setprio(3);
; #pragma unroll
;                 for (int s = 0; s < 16; ++s) {
;                     const float* qn = B + ((MODE & 2) ? 0 : ((s + 1) & 15)) * 384;
;                     const f32x4 nr4 = *(const f32x4*)(qn + c4), nom4 = *(const f32x4*)(qn + 64 + c4), nk4 = *(const f32x4*)(qn + 128 + c4), nkk4 = *(const f32x4*)(qn + 192 + c4), nka4 = *(const f32x4*)(qn + 256 + c4);
;                     const float nv = qn[320 + rowl];
;                     const f32x2 pa = Sa * (f32x2){kk4.x, kk4.y} + Sb * (f32x2){kk4.z, kk4.w};
;                     const float sa = (MODE & 1) ? (pa.x + pa.y) : allreduce16(pa.x + pa.y);
;                     Sa = Sa - Sa * (f32x2){om4.x, om4.y} + (f32x2){k4.x, k4.y} * v; Sb = Sb - Sb * (f32x2){om4.z, om4.w} + (f32x2){k4.z, k4.w} * v;
;                     Sa = Sa - (f32x2){ka4.x, ka4.y} * sa; Sb = Sb - (f32x2){ka4.z, ka4.w} * sa;
;                     const f32x2 py = Sa * (f32x2){r4.x, r4.y} + Sb * (f32x2){r4.z, r4.w};
;                     PY[s * 260] = py.x + py.y;
;                     r4 = nr4; om4 = nom4; k4 = nk4; kk4 = nkk4; ka4 = nka4; v = nv;
;                 }
;                 __builtin_amdgcn_s_setprio(0);
.LBB0_1412:
	s_andn2_saveexec_b64 s[8:9], s[8:9]
	s_cbranch_execz .LBB0_1401
	s_cmp_eq_u32 s6, 0x180000
	s_cbranch_scc1 .LBB0_1401
	s_and_b32 s10, s0, 3
	s_mulk_i32 s10, 0x6000
	s_add_i32 s10, s10, 0
	v_lshl_add_u32 v105, v58, 2, s10
	v_lshl_add_u32 v107, v61, 2, s10
	s_bitcmp1_b32 s0, 0
	s_cselect_b32 s10, 0x4100, 0
	v_add_u32_e32 v63, s10, v60
	s_setprio 3
	ds_read_b128 v[72:75], v105 offset:768
	ds_read_b128 v[68:71], v105 offset:512
	ds_read_b128 v[76:79], v105 offset:1024
	ds_read_b128 v[64:67], v105
	ds_read2st64_b32 v[32:33], v107 offset0:5 offset1:11
	ds_read_b128 v[92:95], v105 offset:2304
	ds_read_b128 v[88:91], v105 offset:2048
	ds_read_b128 v[96:99], v105 offset:2560
	ds_read_b128 v[84:87], v105 offset:1536
	s_waitcnt lgkmcnt(0)
	v_pk_mul_f32 v[28:29], v[54:55], v[72:73]
	v_pk_fma_f32 v[28:29], v[52:53], v[74:75], v[28:29]
	v_add_f32_e32 v28, v28, v29
	s_nop 1
	v_add_f32_dpp v28, v28, v28 quad_perm:[1,0,3,2] row_mask:0xf bank_mask:0xf bound_ctrl:1
	s_nop 1
	v_add_f32_dpp v28, v28, v28 quad_perm:[2,3,0,1] row_mask:0xf bank_mask:0xf bound_ctrl:1
	v_pk_fma_f32 v[24:25], v[68:69], v[32:33], v[54:55] op_sel_hi:[1,0,1]
	v_pk_fma_f32 v[26:27], v[70:71], v[32:33], v[52:53] op_sel_hi:[1,0,1]
	v_add_f32_dpp v28, v28, v28 row_half_mirror row_mask:0xf bank_mask:0xf bound_ctrl:1
	ds_read_b128 v[8:11], v105 offset:3840
	ds_read_b128 v[4:7], v105 offset:3584
	v_add_f32_dpp v28, v28, v28 row_mirror row_mask:0xf bank_mask:0xf bound_ctrl:1
	v_pk_fma_f32 v[24:25], v[76:77], v[28:29], v[24:25] op_sel_hi:[1,0,1] neg_lo:[1,0,0] neg_hi:[1,0,0]
	v_pk_fma_f32 v[26:27], v[78:79], v[28:29], v[26:27] op_sel_hi:[1,0,1] neg_lo:[1,0,0] neg_hi:[1,0,0]
	ds_read_b128 v[12:15], v105 offset:4096
	s_waitcnt lgkmcnt(3)
	v_pk_mul_f32 v[28:29], v[24:25], v[92:93]
	ds_read_b128 v[0:3], v105 offset:3072
	v_pk_fma_f32 v[28:29], v[26:27], v[94:95], v[28:29]
	ds_read2st64_b32 v[34:35], v107 offset0:17 offset1:23
	v_add_f32_e32 v28, v28, v29
	v_pk_mul_f32 v[30:31], v[66:67], v[26:27]
	v_pk_fma_f32 v[30:31], v[64:65], v[24:25], v[30:31]
	v_add_f32_dpp v28, v28, v28 quad_perm:[1,0,3,2] row_mask:0xf bank_mask:0xf bound_ctrl:1
	v_add_f32_e32 v30, v30, v31
	ds_write_b32 v63, v30
	v_add_f32_dpp v28, v28, v28 quad_perm:[2,3,0,1] row_mask:0xf bank_mask:0xf bound_ctrl:1
	v_pk_fma_f32 v[54:55], v[88:89], v[32:33], v[24:25] op_sel:[0,1,0] op_sel_hi:[1,1,1]
	v_pk_fma_f32 v[52:53], v[90:91], v[32:33], v[26:27] op_sel:[0,1,0] op_sel_hi:[1,1,1]
	v_add_f32_dpp v28, v28, v28 row_half_mirror row_mask:0xf bank_mask:0xf bound_ctrl:1
	ds_read_b128 v[72:75], v105 offset:5376
	ds_read_b128 v[68:71], v105 offset:5120
	v_add_f32_dpp v28, v28, v28 row_mirror row_mask:0xf bank_mask:0xf bound_ctrl:1
	v_pk_fma_f32 v[54:55], v[96:97], v[28:29], v[54:55] op_sel_hi:[1,0,1] neg_lo:[1,0,0] neg_hi:[1,0,0]
	v_pk_fma_f32 v[52:53], v[98:99], v[28:29], v[52:53] op_sel_hi:[1,0,1] neg_lo:[1,0,0] neg_hi:[1,0,0]
	ds_read_b128 v[76:79], v105 offset:5632
	s_waitcnt lgkmcnt(4)
	v_pk_mul_f32 v[28:29], v[54:55], v[8:9]
	ds_read_b128 v[64:67], v105 offset:4608
	v_pk_fma_f32 v[28:29], v[52:53], v[10:11], v[28:29]
	v_add_f32_e32 v28, v28, v29
	v_pk_mul_f32 v[30:31], v[86:87], v[52:53]
	v_pk_fma_f32 v[30:31], v[84:85], v[54:55], v[30:31]
	v_add_f32_dpp v28, v28, v28 quad_perm:[1,0,3,2] row_mask:0xf bank_mask:0xf bound_ctrl:1
	v_add_f32_e32 v30, v30, v31
	ds_write_b32 v63, v30 offset:1040
	v_add_f32_dpp v28, v28, v28 quad_perm:[2,3,0,1] row_mask:0xf bank_mask:0xf bound_ctrl:1
	v_pk_fma_f32 v[24:25], v[4:5], v[34:35], v[54:55] op_sel_hi:[1,0,1]
	v_pk_fma_f32 v[26:27], v[6:7], v[34:35], v[52:53] op_sel_hi:[1,0,1]
	v_add_f32_dpp v28, v28, v28 row_half_mirror row_mask:0xf bank_mask:0xf bound_ctrl:1
	ds_read_b128 v[92:95], v105 offset:6912
	ds_read_b128 v[88:91], v105 offset:6656
	v_add_f32_dpp v28, v28, v28 row_mirror row_mask:0xf bank_mask:0xf bound_ctrl:1
	v_pk_fma_f32 v[24:25], v[12:13], v[28:29], v[24:25] op_sel_hi:[1,0,1] neg_lo:[1,0,0] neg_hi:[1,0,0]
	v_pk_fma_f32 v[26:27], v[14:15], v[28:29], v[26:27] op_sel_hi:[1,0,1] neg_lo:[1,0,0] neg_hi:[1,0,0]
	ds_read_b128 v[96:99], v105 offset:7168
	s_waitcnt lgkmcnt(4)
	v_pk_mul_f32 v[28:29], v[24:25], v[72:73]
	ds_read_b128 v[84:87], v105 offset:6144
	v_pk_fma_f32 v[28:29], v[26:27], v[74:75], v[28:29]
	ds_read2st64_b32 v[32:33], v107 offset0:29 offset1:35
	v_add_f32_e32 v28, v28, v29
	v_pk_mul_f32 v[30:31], v[2:3], v[26:27]
	v_pk_fma_f32 v[30:31], v[0:1], v[24:25], v[30:31]
	v_add_f32_dpp v28, v28, v28 quad_perm:[1,0,3,2] row_mask:0xf bank_mask:0xf bound_ctrl:1
	v_add_f32_e32 v30, v30, v31
	ds_write_b32 v63, v30 offset:2080
	v_add_f32_dpp v28, v28, v28 quad_perm:[2,3,0,1] row_mask:0xf bank_mask:0xf bound_ctrl:1
	v_pk_fma_f32 v[54:55], v[68:69], v[34:35], v[24:25] op_sel:[0,1,0] op_sel_hi:[1,1,1]
	v_pk_fma_f32 v[52:53], v[70:71], v[34:35], v[26:27] op_sel:[0,1,0] op_sel_hi:[1,1,1]
	v_add_f32_dpp v28, v28, v28 row_half_mirror row_mask:0xf bank_mask:0xf bound_ctrl:1
	ds_read_b128 v[8:11], v105 offset:8448
	ds_read_b128 v[4:7], v105 offset:8192
	v_add_f32_dpp v28, v28, v28 row_mirror row_mask:0xf bank_mask:0xf bound_ctrl:1
	v_pk_fma_f32 v[54:55], v[76:77], v[28:29], v[54:55] op_sel_hi:[1,0,1] neg_lo:[1,0,0] neg_hi:[1,0,0]
	v_pk_fma_f32 v[52:53], v[78:79], v[28:29], v[52:53] op_sel_hi:[1,0,1] neg_lo:[1,0,0] neg_hi:[1,0,0]
	ds_read_b128 v[12:15], v105 offset:8704
	s_waitcnt lgkmcnt(4)
; __device__ __forceinline__ float allreduce16(float x) { x += dppf<0xB1>(x); x += dppf<0x4E>(x); x += dppf<0x141>(x); x += dppf<0x140>(x); return x; }
; template <int MODE>
; __device__ __forceinline__ void rwkv_scan_unit(int wid_s, const bf16* SIbh_, bf16* Yb_, int ystride, int quarter, float* ldsf) {
;     ...
;                 f32x4 r4 = *(const f32x4*)(q + c4), om4 = *(const f32x4*)(q + 64 + c4), k4 = *(const f32x4*)(q + 128 + c4), kk4 = *(const f32x4*)(q + 192 + c4), ka4 = *(const f32x4*)(q + 256 + c4);
;                 float v = q[320 + rowl];
;                 __builtin_amdgcn_s_setprio(3);
; #pragma unroll
;                 for (int s = 0; s < 16; ++s) {
;                     const float* qn = B + ((MODE & 2) ? 0 : ((s + 1) & 15)) * 384;
;                     const f32x4 nr4 = *(const f32x4*)(qn + c4), nom4 = *(const f32x4*)(qn + 64 + c4), nk4 = *(const f32x4*)(qn + 128 + c4), nkk4 = *(const f32x4*)(qn + 192 + c4), nka4 = *(const f32x4*)(qn + 256 + c4);
;                     const float nv = qn[320 + rowl];
;                     const f32x2 pa = Sa * (f32x2){kk4.x, kk4.y} + Sb * (f32x2){kk4.z, kk4.w};
;                     const float sa = (MODE & 1) ? (pa.x + pa.y) : allreduce16(pa.x + pa.y);
;                     Sa = Sa - Sa * (f32x2){om4.x, om4.y} + (f32x2){k4.x, k4.y} * v; Sb = Sb - Sb * (f32x2){om4.z, om4.w} + (f32x2){k4.z, k4.w} * v;
;                     Sa = Sa - (f32x2){ka4.x, ka4.y} * sa; Sb = Sb - (f32x2){ka4.z, ka4.w} * sa;
;                     const f32x2 py = Sa * (f32x2){r4.x, r4.y} + Sb * (f32x2){r4.z, r4.w};
;                     PY[s * 260] = py.x + py.y;
;                     r4 = nr4; om4 = nom4; k4 = nk4; kk4 = nkk4; ka4 = nka4; v = nv;
;                 }
;                 __builtin_amdgcn_s_setprio(0);
	v_pk_mul_f32 v[28:29], v[54:55], v[92:93]
	ds_read_b128 v[0:3], v105 offset:7680
	v_pk_fma_f32 v[28:29], v[52:53], v[94:95], v[28:29]
	v_add_f32_e32 v28, v28, v29
	v_pk_mul_f32 v[30:31], v[66:67], v[52:53]
	v_pk_fma_f32 v[30:31], v[64:65], v[54:55], v[30:31]
	v_add_f32_dpp v28, v28, v28 quad_perm:[1,0,3,2] row_mask:0xf bank_mask:0xf bound_ctrl:1
	v_add_f32_e32 v30, v30, v31
	ds_write_b32 v63, v30 offset:3120
	v_add_f32_dpp v28, v28, v28 quad_perm:[2,3,0,1] row_mask:0xf bank_mask:0xf bound_ctrl:1
	v_pk_fma_f32 v[24:25], v[88:89], v[32:33], v[54:55] op_sel_hi:[1,0,1]
	v_pk_fma_f32 v[26:27], v[90:91], v[32:33], v[52:53] op_sel_hi:[1,0,1]
	v_add_f32_dpp v28, v28, v28 row_half_mirror row_mask:0xf bank_mask:0xf bound_ctrl:1
	ds_read_b128 v[72:75], v105 offset:9984
	ds_read_b128 v[68:71], v105 offset:9728
	v_add_f32_dpp v28, v28, v28 row_mirror row_mask:0xf bank_mask:0xf bound_ctrl:1
	v_pk_fma_f32 v[24:25], v[96:97], v[28:29], v[24:25] op_sel_hi:[1,0,1] neg_lo:[1,0,0] neg_hi:[1,0,0]
	v_pk_fma_f32 v[26:27], v[98:99], v[28:29], v[26:27] op_sel_hi:[1,0,1] neg_lo:[1,0,0] neg_hi:[1,0,0]
	ds_read_b128 v[76:79], v105 offset:10240
	s_waitcnt lgkmcnt(4)
	v_pk_mul_f32 v[28:29], v[24:25], v[8:9]
	ds_read_b128 v[64:67], v105 offset:9216
	v_pk_fma_f32 v[28:29], v[26:27], v[10:11], v[28:29]
	ds_read2st64_b32 v[34:35], v107 offset0:41 offset1:47
	v_add_f32_e32 v28, v28, v29
	v_pk_mul_f32 v[30:31], v[86:87], v[26:27]
	v_pk_fma_f32 v[30:31], v[84:85], v[24:25], v[30:31]
	v_add_f32_dpp v28, v28, v28 quad_perm:[1,0,3,2] row_mask:0xf bank_mask:0xf bound_ctrl:1
	v_add_f32_e32 v30, v30, v31
	ds_write_b32 v63, v30 offset:4160
	v_add_f32_dpp v28, v28, v28 quad_perm:[2,3,0,1] row_mask:0xf bank_mask:0xf bound_ctrl:1
	v_pk_fma_f32 v[54:55], v[4:5], v[32:33], v[24:25] op_sel:[0,1,0] op_sel_hi:[1,1,1]
	v_pk_fma_f32 v[52:53], v[6:7], v[32:33], v[26:27] op_sel:[0,1,0] op_sel_hi:[1,1,1]
	v_add_f32_dpp v28, v28, v28 row_half_mirror row_mask:0xf bank_mask:0xf bound_ctrl:1
	ds_read_b128 v[92:95], v105 offset:11520
	ds_read_b128 v[88:91], v105 offset:11264
	v_add_f32_dpp v28, v28, v28 row_mirror row_mask:0xf bank_mask:0xf bound_ctrl:1
	v_pk_fma_f32 v[54:55], v[12:13], v[28:29], v[54:55] op_sel_hi:[1,0,1] neg_lo:[1,0,0] neg_hi:[1,0,0]
	v_pk_fma_f32 v[52:53], v[14:15], v[28:29], v[52:53] op_sel_hi:[1,0,1] neg_lo:[1,0,0] neg_hi:[1,0,0]
	ds_read_b128 v[96:99], v105 offset:11776
	s_waitcnt lgkmcnt(4)
	v_pk_mul_f32 v[28:29], v[54:55], v[72:73]
	ds_read_b128 v[84:87], v105 offset:10752
	v_pk_fma_f32 v[28:29], v[52:53], v[74:75], v[28:29]
	v_add_f32_e32 v28, v28, v29
	v_pk_mul_f32 v[30:31], v[2:3], v[52:53]
	v_pk_fma_f32 v[30:31], v[0:1], v[54:55], v[30:31]
	v_add_f32_dpp v28, v28, v28 quad_perm:[1,0,3,2] row_mask:0xf bank_mask:0xf bound_ctrl:1
	v_add_f32_e32 v30, v30, v31
	ds_write_b32 v63, v30 offset:5200
	v_add_f32_dpp v28, v28, v28 quad_perm:[2,3,0,1] row_mask:0xf bank_mask:0xf bound_ctrl:1
	v_pk_fma_f32 v[24:25], v[68:69], v[34:35], v[54:55] op_sel_hi:[1,0,1]
	v_pk_fma_f32 v[26:27], v[70:71], v[34:35], v[52:53] op_sel_hi:[1,0,1]
	v_add_f32_dpp v28, v28, v28 row_half_mirror row_mask:0xf bank_mask:0xf bound_ctrl:1
	ds_read_b128 v[8:11], v105 offset:13056
	ds_read_b128 v[4:7], v105 offset:12800
	v_add_f32_dpp v28, v28, v28 row_mirror row_mask:0xf bank_mask:0xf bound_ctrl:1
	v_pk_fma_f32 v[24:25], v[76:77], v[28:29], v[24:25] op_sel_hi:[1,0,1] neg_lo:[1,0,0] neg_hi:[1,0,0]
	v_pk_fma_f32 v[26:27], v[78:79], v[28:29], v[26:27] op_sel_hi:[1,0,1] neg_lo:[1,0,0] neg_hi:[1,0,0]
	ds_read_b128 v[12:15], v105 offset:13312
	s_waitcnt lgkmcnt(4)
	v_pk_mul_f32 v[28:29], v[24:25], v[92:93]
	ds_read_b128 v[0:3], v105 offset:12288
	v_pk_fma_f32 v[28:29], v[26:27], v[94:95], v[28:29]
	ds_read2st64_b32 v[32:33], v107 offset0:53 offset1:59
	v_add_f32_e32 v28, v28, v29
	v_pk_mul_f32 v[30:31], v[66:67], v[26:27]
	v_pk_fma_f32 v[30:31], v[64:65], v[24:25], v[30:31]
	v_add_f32_dpp v28, v28, v28 quad_perm:[1,0,3,2] row_mask:0xf bank_mask:0xf bound_ctrl:1
	v_add_f32_e32 v30, v30, v31
	ds_write_b32 v63, v30 offset:6240
	v_add_f32_dpp v28, v28, v28 quad_perm:[2,3,0,1] row_mask:0xf bank_mask:0xf bound_ctrl:1
	v_pk_fma_f32 v[54:55], v[88:89], v[34:35], v[24:25] op_sel:[0,1,0] op_sel_hi:[1,1,1]
	v_pk_fma_f32 v[52:53], v[90:91], v[34:35], v[26:27] op_sel:[0,1,0] op_sel_hi:[1,1,1]
	v_add_f32_dpp v28, v28, v28 row_half_mirror row_mask:0xf bank_mask:0xf bound_ctrl:1
	ds_read_b128 v[72:75], v105 offset:14592
	ds_read_b128 v[68:71], v105 offset:14336
	v_add_f32_dpp v28, v28, v28 row_mirror row_mask:0xf bank_mask:0xf bound_ctrl:1
	v_pk_fma_f32 v[54:55], v[96:97], v[28:29], v[54:55] op_sel_hi:[1,0,1] neg_lo:[1,0,0] neg_hi:[1,0,0]
	v_pk_fma_f32 v[52:53], v[98:99], v[28:29], v[52:53] op_sel_hi:[1,0,1] neg_lo:[1,0,0] neg_hi:[1,0,0]
	ds_read_b128 v[76:79], v105 offset:14848
	s_waitcnt lgkmcnt(4)
	v_pk_mul_f32 v[28:29], v[54:55], v[8:9]
	ds_read_b128 v[64:67], v105 offset:13824
	v_pk_fma_f32 v[28:29], v[52:53], v[10:11], v[28:29]
	v_add_f32_e32 v28, v28, v29
	v_pk_mul_f32 v[30:31], v[86:87], v[52:53]
	v_pk_fma_f32 v[30:31], v[84:85], v[54:55], v[30:31]
	v_add_f32_dpp v28, v28, v28 quad_perm:[1,0,3,2] row_mask:0xf bank_mask:0xf bound_ctrl:1
	v_add_f32_e32 v30, v30, v31
	ds_write_b32 v63, v30 offset:7280
	v_add_f32_dpp v28, v28, v28 quad_perm:[2,3,0,1] row_mask:0xf bank_mask:0xf bound_ctrl:1
	v_pk_fma_f32 v[24:25], v[4:5], v[32:33], v[54:55] op_sel_hi:[1,0,1]
	v_pk_fma_f32 v[26:27], v[6:7], v[32:33], v[52:53] op_sel_hi:[1,0,1]
	v_add_f32_dpp v28, v28, v28 row_half_mirror row_mask:0xf bank_mask:0xf bound_ctrl:1
	ds_read_b128 v[92:95], v105 offset:16128
	ds_read_b128 v[88:91], v105 offset:15872
	v_add_f32_dpp v28, v28, v28 row_mirror row_mask:0xf bank_mask:0xf bound_ctrl:1
	v_pk_fma_f32 v[24:25], v[12:13], v[28:29], v[24:25] op_sel_hi:[1,0,1] neg_lo:[1,0,0] neg_hi:[1,0,0]
	v_pk_fma_f32 v[26:27], v[14:15], v[28:29], v[26:27] op_sel_hi:[1,0,1] neg_lo:[1,0,0] neg_hi:[1,0,0]
	ds_read_b128 v[96:99], v105 offset:16384
	s_waitcnt lgkmcnt(4)
; __device__ __forceinline__ float allreduce16(float x) { x += dppf<0xB1>(x); x += dppf<0x4E>(x); x += dppf<0x141>(x); x += dppf<0x140>(x); return x; }
; template <int MODE>
; __device__ __forceinline__ void rwkv_scan_unit(int wid_s, const bf16* SIbh_, bf16* Yb_, int ystride, int quarter, float* ldsf) {
;     ...
;                 f32x4 r4 = *(const f32x4*)(q + c4), om4 = *(const f32x4*)(q + 64 + c4), k4 = *(const f32x4*)(q + 128 + c4), kk4 = *(const f32x4*)(q + 192 + c4), ka4 = *(const f32x4*)(q + 256 + c4);
;                 float v = q[320 + rowl];
;                 __builtin_amdgcn_s_setprio(3);
; #pragma unroll
;                 for (int s = 0; s < 16; ++s) {
;                     const float* qn = B + ((MODE & 2) ? 0 : ((s + 1) & 15)) * 384;
;                     const f32x4 nr4 = *(const f32x4*)(qn + c4), nom4 = *(const f32x4*)(qn + 64 + c4), nk4 = *(const f32x4*)(qn + 128 + c4), nkk4 = *(const f32x4*)(qn + 192 + c4), nka4 = *(const f32x4*)(qn + 256 + c4);
;                     const float nv = qn[320 + rowl];
;                     const f32x2 pa = Sa * (f32x2){kk4.x, kk4.y} + Sb * (f32x2){kk4.z, kk4.w};
;                     const float sa = (MODE & 1) ? (pa.x + pa.y) : allreduce16(pa.x + pa.y);
;                     Sa = Sa - Sa * (f32x2){om4.x, om4.y} + (f32x2){k4.x, k4.y} * v; Sb = Sb - Sb * (f32x2){om4.z, om4.w} + (f32x2){k4.z, k4.w} * v;
;                     Sa = Sa - (f32x2){ka4.x, ka4.y} * sa; Sb = Sb - (f32x2){ka4.z, ka4.w} * sa;
;                     const f32x2 py = Sa * (f32x2){r4.x, r4.y} + Sb * (f32x2){r4.z, r4.w};
;                     PY[s * 260] = py.x + py.y;
;                     r4 = nr4; om4 = nom4; k4 = nk4; kk4 = nkk4; ka4 = nka4; v = nv;
;                 }
;                 __builtin_amdgcn_s_setprio(0);
	v_pk_mul_f32 v[28:29], v[24:25], v[72:73]
	ds_read_b128 v[84:87], v105 offset:15360
	v_pk_fma_f32 v[28:29], v[26:27], v[74:75], v[28:29]
	ds_read2st64_b32 v[34:35], v107 offset0:65 offset1:71
	v_add_f32_e32 v28, v28, v29
	v_pk_mul_f32 v[30:31], v[2:3], v[26:27]
	v_pk_fma_f32 v[30:31], v[0:1], v[24:25], v[30:31]
	v_add_f32_dpp v28, v28, v28 quad_perm:[1,0,3,2] row_mask:0xf bank_mask:0xf bound_ctrl:1
	v_add_f32_e32 v30, v30, v31
	ds_write_b32 v63, v30 offset:8320
	v_add_f32_dpp v28, v28, v28 quad_perm:[2,3,0,1] row_mask:0xf bank_mask:0xf bound_ctrl:1
	v_pk_fma_f32 v[54:55], v[68:69], v[32:33], v[24:25] op_sel:[0,1,0] op_sel_hi:[1,1,1]
	v_pk_fma_f32 v[52:53], v[70:71], v[32:33], v[26:27] op_sel:[0,1,0] op_sel_hi:[1,1,1]
	v_add_f32_dpp v28, v28, v28 row_half_mirror row_mask:0xf bank_mask:0xf bound_ctrl:1
	ds_read_b128 v[8:11], v105 offset:17664
	ds_read_b128 v[4:7], v105 offset:17408
	v_add_f32_dpp v28, v28, v28 row_mirror row_mask:0xf bank_mask:0xf bound_ctrl:1
	v_pk_fma_f32 v[54:55], v[76:77], v[28:29], v[54:55] op_sel_hi:[1,0,1] neg_lo:[1,0,0] neg_hi:[1,0,0]
	v_pk_fma_f32 v[52:53], v[78:79], v[28:29], v[52:53] op_sel_hi:[1,0,1] neg_lo:[1,0,0] neg_hi:[1,0,0]
	ds_read_b128 v[12:15], v105 offset:17920
	s_waitcnt lgkmcnt(4)
	v_pk_mul_f32 v[28:29], v[54:55], v[92:93]
	ds_read_b128 v[0:3], v105 offset:16896
	v_pk_fma_f32 v[28:29], v[52:53], v[94:95], v[28:29]
	v_add_f32_e32 v28, v28, v29
	v_pk_mul_f32 v[30:31], v[66:67], v[52:53]
	v_pk_fma_f32 v[30:31], v[64:65], v[54:55], v[30:31]
	v_add_f32_dpp v28, v28, v28 quad_perm:[1,0,3,2] row_mask:0xf bank_mask:0xf bound_ctrl:1
	v_add_f32_e32 v30, v30, v31
	ds_write_b32 v63, v30 offset:9360
	v_add_f32_dpp v28, v28, v28 quad_perm:[2,3,0,1] row_mask:0xf bank_mask:0xf bound_ctrl:1
	v_pk_fma_f32 v[24:25], v[88:89], v[34:35], v[54:55] op_sel_hi:[1,0,1]
	v_pk_fma_f32 v[26:27], v[90:91], v[34:35], v[52:53] op_sel_hi:[1,0,1]
	v_add_f32_dpp v28, v28, v28 row_half_mirror row_mask:0xf bank_mask:0xf bound_ctrl:1
	ds_read_b128 v[72:75], v105 offset:19200
	ds_read_b128 v[68:71], v105 offset:18944
	v_add_f32_dpp v28, v28, v28 row_mirror row_mask:0xf bank_mask:0xf bound_ctrl:1
	v_pk_fma_f32 v[24:25], v[96:97], v[28:29], v[24:25] op_sel_hi:[1,0,1] neg_lo:[1,0,0] neg_hi:[1,0,0]
	v_pk_fma_f32 v[26:27], v[98:99], v[28:29], v[26:27] op_sel_hi:[1,0,1] neg_lo:[1,0,0] neg_hi:[1,0,0]
	ds_read_b128 v[76:79], v105 offset:19456
	s_waitcnt lgkmcnt(4)
	v_pk_mul_f32 v[28:29], v[24:25], v[8:9]
	ds_read_b128 v[64:67], v105 offset:18432
	v_pk_fma_f32 v[28:29], v[26:27], v[10:11], v[28:29]
	ds_read2st64_b32 v[32:33], v107 offset0:77 offset1:83
	v_add_f32_e32 v28, v28, v29
	v_pk_mul_f32 v[30:31], v[86:87], v[26:27]
	v_pk_fma_f32 v[30:31], v[84:85], v[24:25], v[30:31]
	v_add_f32_dpp v28, v28, v28 quad_perm:[1,0,3,2] row_mask:0xf bank_mask:0xf bound_ctrl:1
	v_add_f32_e32 v30, v30, v31
	ds_write_b32 v63, v30 offset:10400
	v_add_f32_dpp v28, v28, v28 quad_perm:[2,3,0,1] row_mask:0xf bank_mask:0xf bound_ctrl:1
	v_pk_fma_f32 v[54:55], v[4:5], v[34:35], v[24:25] op_sel:[0,1,0] op_sel_hi:[1,1,1]
	v_pk_fma_f32 v[52:53], v[6:7], v[34:35], v[26:27] op_sel:[0,1,0] op_sel_hi:[1,1,1]
	v_add_f32_dpp v28, v28, v28 row_half_mirror row_mask:0xf bank_mask:0xf bound_ctrl:1
	ds_read_b128 v[92:95], v105 offset:20736
	ds_read_b128 v[88:91], v105 offset:20480
	v_add_f32_dpp v28, v28, v28 row_mirror row_mask:0xf bank_mask:0xf bound_ctrl:1
	v_pk_fma_f32 v[54:55], v[12:13], v[28:29], v[54:55] op_sel_hi:[1,0,1] neg_lo:[1,0,0] neg_hi:[1,0,0]
	v_pk_fma_f32 v[52:53], v[14:15], v[28:29], v[52:53] op_sel_hi:[1,0,1] neg_lo:[1,0,0] neg_hi:[1,0,0]
	ds_read_b128 v[96:99], v105 offset:20992
	s_waitcnt lgkmcnt(4)
; __device__ __forceinline__ float allreduce16(float x) { x += dppf<0xB1>(x); x += dppf<0x4E>(x); x += dppf<0x141>(x); x += dppf<0x140>(x); return x; }
; template <int MODE>
; __device__ __forceinline__ void rwkv_scan_unit(int wid_s, const bf16* SIbh_, bf16* Yb_, int ystride, int quarter, float* ldsf) {
;     ...
;                 f32x4 r4 = *(const f32x4*)(q + c4), om4 = *(const f32x4*)(q + 64 + c4), k4 = *(const f32x4*)(q + 128 + c4), kk4 = *(const f32x4*)(q + 192 + c4), ka4 = *(const f32x4*)(q + 256 + c4);
;                 float v = q[320 + rowl];
;                 __builtin_amdgcn_s_setprio(3);
; #pragma unroll
;                 for (int s = 0; s < 16; ++s) {
;                     const float* qn = B + ((MODE & 2) ? 0 : ((s + 1) & 15)) * 384;
;                     const f32x4 nr4 = *(const f32x4*)(qn + c4), nom4 = *(const f32x4*)(qn + 64 + c4), nk4 = *(const f32x4*)(qn + 128 + c4), nkk4 = *(const f32x4*)(qn + 192 + c4), nka4 = *(const f32x4*)(qn + 256 + c4);
;                     const float nv = qn[320 + rowl];
;                     const f32x2 pa = Sa * (f32x2){kk4.x, kk4.y} + Sb * (f32x2){kk4.z, kk4.w};
;                     const float sa = (MODE & 1) ? (pa.x + pa.y) : allreduce16(pa.x + pa.y);
;                     Sa = Sa - Sa * (f32x2){om4.x, om4.y} + (f32x2){k4.x, k4.y} * v; Sb = Sb - Sb * (f32x2){om4.z, om4.w} + (f32x2){k4.z, k4.w} * v;
;                     Sa = Sa - (f32x2){ka4.x, ka4.y} * sa; Sb = Sb - (f32x2){ka4.z, ka4.w} * sa;
;                     const f32x2 py = Sa * (f32x2){r4.x, r4.y} + Sb * (f32x2){r4.z, r4.w};
;                     PY[s * 260] = py.x + py.y;
;                     r4 = nr4; om4 = nom4; k4 = nk4; kk4 = nkk4; ka4 = nka4; v = nv;
;                 }
;                 __builtin_amdgcn_s_setprio(0);
	v_pk_mul_f32 v[28:29], v[54:55], v[72:73]
	ds_read_b128 v[84:87], v105 offset:19968
	v_pk_fma_f32 v[28:29], v[52:53], v[74:75], v[28:29]
	v_add_f32_e32 v28, v28, v29
	v_pk_mul_f32 v[30:31], v[2:3], v[52:53]
	v_pk_fma_f32 v[30:31], v[0:1], v[54:55], v[30:31]
	v_add_f32_dpp v28, v28, v28 quad_perm:[1,0,3,2] row_mask:0xf bank_mask:0xf bound_ctrl:1
	v_add_f32_e32 v30, v30, v31
	ds_write_b32 v63, v30 offset:11440
	v_add_f32_dpp v28, v28, v28 quad_perm:[2,3,0,1] row_mask:0xf bank_mask:0xf bound_ctrl:1
	v_pk_fma_f32 v[24:25], v[68:69], v[32:33], v[54:55] op_sel_hi:[1,0,1]
	v_pk_fma_f32 v[26:27], v[70:71], v[32:33], v[52:53] op_sel_hi:[1,0,1]
	v_add_f32_dpp v28, v28, v28 row_half_mirror row_mask:0xf bank_mask:0xf bound_ctrl:1
	ds_read_b128 v[8:11], v105 offset:22272
	ds_read_b128 v[4:7], v105 offset:22016
	v_add_f32_dpp v28, v28, v28 row_mirror row_mask:0xf bank_mask:0xf bound_ctrl:1
	v_pk_fma_f32 v[24:25], v[76:77], v[28:29], v[24:25] op_sel_hi:[1,0,1] neg_lo:[1,0,0] neg_hi:[1,0,0]
	v_pk_fma_f32 v[26:27], v[78:79], v[28:29], v[26:27] op_sel_hi:[1,0,1] neg_lo:[1,0,0] neg_hi:[1,0,0]
	ds_read_b128 v[12:15], v105 offset:22528
	s_waitcnt lgkmcnt(4)
	v_pk_mul_f32 v[28:29], v[24:25], v[92:93]
	ds_read_b128 v[0:3], v105 offset:21504
	v_pk_fma_f32 v[28:29], v[26:27], v[94:95], v[28:29]
	ds_read2st64_b32 v[34:35], v107 offset0:89 offset1:95
	v_add_f32_e32 v28, v28, v29
	v_pk_mul_f32 v[30:31], v[66:67], v[26:27]
	v_pk_fma_f32 v[30:31], v[64:65], v[24:25], v[30:31]
	v_add_f32_dpp v28, v28, v28 quad_perm:[1,0,3,2] row_mask:0xf bank_mask:0xf bound_ctrl:1
	v_add_f32_e32 v30, v30, v31
	ds_write_b32 v63, v30 offset:12480
	v_add_f32_dpp v28, v28, v28 quad_perm:[2,3,0,1] row_mask:0xf bank_mask:0xf bound_ctrl:1
	v_pk_fma_f32 v[54:55], v[88:89], v[32:33], v[24:25] op_sel:[0,1,0] op_sel_hi:[1,1,1]
	v_pk_fma_f32 v[52:53], v[90:91], v[32:33], v[26:27] op_sel:[0,1,0] op_sel_hi:[1,1,1]
	v_add_f32_dpp v28, v28, v28 row_half_mirror row_mask:0xf bank_mask:0xf bound_ctrl:1
	ds_read_b128 v[72:75], v105 offset:23808
	ds_read_b128 v[68:71], v105 offset:23552
	v_add_f32_dpp v28, v28, v28 row_mirror row_mask:0xf bank_mask:0xf bound_ctrl:1
	v_pk_fma_f32 v[54:55], v[96:97], v[28:29], v[54:55] op_sel_hi:[1,0,1] neg_lo:[1,0,0] neg_hi:[1,0,0]
	v_pk_fma_f32 v[52:53], v[98:99], v[28:29], v[52:53] op_sel_hi:[1,0,1] neg_lo:[1,0,0] neg_hi:[1,0,0]
	ds_read_b128 v[76:79], v105 offset:24064
	ds_read_b128 v[36:39], v105 offset:23296
	s_waitcnt lgkmcnt(5)
	v_pk_mul_f32 v[28:29], v[54:55], v[8:9]
	ds_read_b128 v[64:67], v105 offset:23040
	v_pk_fma_f32 v[28:29], v[52:53], v[10:11], v[28:29]
	v_add_f32_e32 v28, v28, v29
	v_pk_mul_f32 v[30:31], v[86:87], v[52:53]
	v_pk_fma_f32 v[30:31], v[84:85], v[54:55], v[30:31]
	v_add_f32_dpp v28, v28, v28 quad_perm:[1,0,3,2] row_mask:0xf bank_mask:0xf bound_ctrl:1
	v_add_f32_e32 v30, v30, v31
	ds_write_b32 v63, v30 offset:13520
	v_add_f32_dpp v28, v28, v28 quad_perm:[2,3,0,1] row_mask:0xf bank_mask:0xf bound_ctrl:1
	v_pk_fma_f32 v[24:25], v[4:5], v[34:35], v[54:55] op_sel_hi:[1,0,1]
	v_pk_fma_f32 v[26:27], v[6:7], v[34:35], v[52:53] op_sel_hi:[1,0,1]
	v_add_f32_dpp v28, v28, v28 row_half_mirror row_mask:0xf bank_mask:0xf bound_ctrl:1
	s_nop 1
	v_add_f32_dpp v28, v28, v28 row_mirror row_mask:0xf bank_mask:0xf bound_ctrl:1
	v_pk_fma_f32 v[24:25], v[12:13], v[28:29], v[24:25] op_sel_hi:[1,0,1] neg_lo:[1,0,0] neg_hi:[1,0,0]
	v_pk_fma_f32 v[26:27], v[14:15], v[28:29], v[26:27] op_sel_hi:[1,0,1] neg_lo:[1,0,0] neg_hi:[1,0,0]
	s_waitcnt lgkmcnt(1)
	v_pk_mul_f32 v[28:29], v[24:25], v[72:73]
	v_pk_fma_f32 v[28:29], v[26:27], v[74:75], v[28:29]
	v_add_f32_e32 v28, v28, v29
	v_pk_mul_f32 v[30:31], v[2:3], v[26:27]
	v_pk_fma_f32 v[30:31], v[0:1], v[24:25], v[30:31]
	v_add_f32_dpp v28, v28, v28 quad_perm:[1,0,3,2] row_mask:0xf bank_mask:0xf bound_ctrl:1
	v_add_f32_e32 v30, v30, v31
	ds_write_b32 v63, v30 offset:14560
	v_add_f32_dpp v28, v28, v28 quad_perm:[2,3,0,1] row_mask:0xf bank_mask:0xf bound_ctrl:1
	v_pk_fma_f32 v[54:55], v[68:69], v[34:35], v[24:25] op_sel:[0,1,0] op_sel_hi:[1,1,1]
	v_pk_fma_f32 v[52:53], v[70:71], v[34:35], v[26:27] op_sel:[0,1,0] op_sel_hi:[1,1,1]
	v_add_f32_dpp v28, v28, v28 row_half_mirror row_mask:0xf bank_mask:0xf bound_ctrl:1
	s_nop 1
	v_add_f32_dpp v28, v28, v28 row_mirror row_mask:0xf bank_mask:0xf bound_ctrl:1
	v_pk_fma_f32 v[54:55], v[76:77], v[28:29], v[54:55] op_sel_hi:[1,0,1] neg_lo:[1,0,0] neg_hi:[1,0,0]
	v_pk_fma_f32 v[52:53], v[78:79], v[28:29], v[52:53] op_sel_hi:[1,0,1] neg_lo:[1,0,0] neg_hi:[1,0,0]
	s_waitcnt lgkmcnt(1)
	v_pk_mul_f32 v[30:31], v[66:67], v[52:53]
	v_pk_fma_f32 v[30:31], v[64:65], v[54:55], v[30:31]
	v_pk_mul_f32 v[54:55], v[54:55], v[36:37]
	v_pk_mul_f32 v[52:53], v[52:53], v[38:39]
	v_add_f32_e32 v30, v30, v31
	ds_write_b32 v63, v30 offset:15600
	s_setprio 0
	s_branch .LBB0_1401
